# one static s_setprio 1 for waves 4-7 at the attention phase entry (younger-half priority raise)
# baseline (speedup 1.0000x reference)
; #define LAS __attribute__((address_space(3)))
; template<int THRL> __device__ __forceinline__ void attn_unit(int b,int hc,int qb,const bf16*Q,const bf16*__restrict__ K,const bf16*__restrict__ V,bf16*O,char*shm){
;   const int tid=threadIdx.x,lane=tid&63,r32=lane&31,hi=lane>>5; const int wid=__builtin_amdgcn_readfirstlane(tid>>6);
;   const long rowbase=(long)b*SEQ; const int q0=qb*QB;
;   const bf16*Qw=Q+(rowbase+q0+wid*QBLK)*DM+hc*D;
;   const lds_cfptr btab=(lds_cfptr)((lds_cptr)shm+LDS_BIAS);
;   const unsigned lds0=(unsigned)(uintptr_t)shm;
;   float*wsf=(float*)(shm+LDS_WS)+wid*64;
;   const bf16*ksrc=K+(long)((b*16+hc)*128)*4096+wid*512+lane*8;
;   const bf16*vsrc=V+(long)((b*8+(hc>>1))*128)*8192+wid*512+lane*8;
;   const unsigned kdst=lds0+LDS_K+wid*1024, vdst=lds0+LDS_V+wid*1024;
;     ...
;   const int vb0=(int)(lds0+LDS_V)+((lane>>4)&1)*32+(lane&3)*8+(4*hi+((lane&15)>>2))*64;
;   const char*Kbase=shm+LDS_K; bf16x8 kf[8];
;   const lds_cptr shm3=(lds_cptr)shm; const lds_cptr kp0=shm3+LDS_K+hi*1024+r32*16; const lds_cptr vp0=shm3+LDS_V+((lane>>4)&1)*32+(lane&3)*8+(4*hi+((lane&15)>>2))*64;
;   const int NT=(q0+QB)/KVBLK;
; __global__ void __launch_bounds__(NWAVES * 64, 2) mega_fwd(Args args) {
;     ...
;         __syncthreads();
;         { const float* bt = (const float*)(ws + WS_BT) + ((vcu >> 3) & 7) * 128; LAS float* dst = (LAS float*)(lds + attn_body::LDS_BIAS);
;           for (int i = tid; i < 1024; i += NWAVES * 64) { const int d = i - 256; dst[i] = d < 0 ? -__builtin_inff() : bt[d > 127 ? 127 : d]; } }
;         asm volatile("s_waitcnt vmcnt(0) lgkmcnt(0)" ::: "memory"); __syncthreads();
;         const attn_body::AttnTensors AT{(const attn_body::bf16*)(ws + WS_Q), (const attn_body::bf16*)(ws + WS_K), (const attn_body::bf16*)(ws + WS_V), (attn_body::bf16*)(ws + WS_HBA), (attn_body::bf16*)(ws + WS_O1)};
;         const attn_body::StaticOrder S(G, bx);
;     ...
;         attn_body::attn_phase<attn_body::StaticOrder>((char*)lds_raw, AT, S);
.LBB0_1229:
	s_or_b64 exec, exec, s[2:3]
	v_readfirstlane_b32 s0, v208
	s_nop 3
	s_lshr_b32 s0, s0, 6
	s_cmp_ge_u32 s0, 4
	s_cbranch_scc0 .Lprio_attn_done
	s_setprio 1
.Lprio_attn_done:
	s_add_u32 s33, s28, 0xe000000
	s_addc_u32 s58, s29, 0
	s_add_u32 s59, s28, 0x12000000
	s_addc_u32 s60, s29, 0
	s_add_u32 s61, s28, 0x16000000
	s_addc_u32 s62, s29, 0
	s_add_u32 s6, s28, 0x1a000000
	s_addc_u32 s7, s29, 0
	v_readlane_b32 s2, v255, 4
	s_ashr_i32 s1, s20, 31
	s_ashr_i32 s0, s2, 31
	s_lshr_b32 s1, s1, 29
	s_lshr_b32 s0, s0, 29
	s_add_i32 s1, s20, s1
	s_add_i32 s0, s2, s0
	s_and_b32 s2, s1, -8
	s_ashr_i32 s0, s0, 3
	s_sub_i32 s2, s20, s2
	s_mul_i32 s0, s0, s2
	s_ashr_i32 s1, s1, 3
	s_add_i32 s0, s0, s1
	s_and_b32 s63, s0, 7
	s_ashr_i32 s1, s0, 2
	s_lshr_b32 s0, s0, 2
	s_and_b32 s1, s1, -16
	s_and_b32 s0, s0, 14
	v_lshlrev_b32_e32 v2, 1, v208
	v_lshlrev_b32_e32 v211, 4, v208
	s_or_b32 s64, s1, s0
	s_xor_b32 s65, s63, 15
	s_or_b32 s68, s63, 16
	s_xor_b32 s69, s63, 31
	v_and_b32_e32 v212, 31, v208
	v_lshrrev_b32_e32 v1, 5, v209
	v_and_b32_e32 v3, 32, v2
	v_lshlrev_b32_e32 v4, 3, v208
	v_and_b32_e32 v2, 0xc0, v211
	s_cmp_lg_u32 0, -1
	v_and_b32_e32 v5, 24, v4
	v_lshl_or_b32 v6, v1, 8, v2
	v_lshlrev_b32_e32 v2, 10, v212
	s_cselect_b32 s0, 0, 0
	v_lshlrev_b32_e32 v7, 10, v1
	v_lshl_or_b32 v2, v1, 3, v2
	v_lshlrev_b32_e32 v215, 2, v1
	v_lshlrev_b32_e32 v216, 4, v1
	v_lshlrev_b32_e32 v217, 9, v1
	v_or_b32_e32 v1, v5, v6
	s_addk_i32 s0, 0x6000
	v_add3_u32 v228, v3, s0, v1
	v_sub_u32_e32 v1, v212, v215
	v_mov_b32_e32 v197, 0
	v_add_u32_e32 v9, 0, v3
	v_lshlrev_b32_e32 v196, 4, v209
	v_add_u32_e32 v229, 0xfffffec0, v1
	v_lshlrev_b32_e32 v1, 2, v212
	s_waitcnt vmcnt(0) lgkmcnt(0)
	v_add3_u32 v214, v9, v5, v6
	v_lshrrev_b32_e32 v210, 3, v209
	v_and_b32_e32 v218, 56, v4
	v_bfe_u32 v219, v4, 5, 1
	v_lshl_add_u64 v[4:5], s[28:29], 0, v[196:197]
	s_mov_b64 s[0:1], 0x1600c000
	v_sub_u32_e32 v1, v1, v216
	v_readlane_b32 s3, v255, 5
	v_lshlrev_b32_e32 v0, 3, v209
	v_lshlrev_b32_e32 v8, 4, v212
	v_or_b32_e32 v222, 8, v210
	v_or_b32_e32 v224, 16, v210
	v_or_b32_e32 v226, 24, v210
	v_lshl_add_u64 v[198:199], v[4:5], 0, s[0:1]
	v_add_u32_e32 v1, 0, v1
	s_mov_b64 s[0:1], 0x16004000
	s_movk_i32 s44, 0xe000
	s_mov_b32 s13, 0
	v_add3_u32 v213, 0, v7, v8
	v_cmp_gt_u32_e64 s[2:3], 32, v209
	v_and_b32_e32 v220, 48, v211
	v_lshlrev_b32_e32 v221, 7, v210
	v_lshlrev_b32_e32 v223, 7, v222
	v_lshlrev_b32_e32 v225, 7, v224
	v_lshlrev_b32_e32 v227, 7, v226
	v_add_u32_e32 v230, 0x1a614, v1
	v_lshl_add_u64 v[200:201], v[4:5], 0, s[0:1]
	v_lshlrev_b32_e32 v196, 1, v0
	s_mov_b64 s[14:15], 0x2000
	v_lshlrev_b32_e32 v231, 1, v2
	s_mov_b64 s[16:17], 0x4000
	s_add_i32 s70, 0, 0x1a800
	s_mov_b64 s[24:25], 0x6000
	s_mov_b32 s45, -1
	s_mov_b32 s71, 0x41000000
	s_mov_b64 s[46:47], 0x8000
	s_movk_i32 s72, 0xef
	s_movk_i32 s73, 0xf0
	s_movk_i32 s74, 0xf1
	s_movk_i32 s75, 0xf2
	s_movk_i32 s76, 0xf7
	s_movk_i32 s77, 0xf8
	s_movk_i32 s78, 0xf9
	s_movk_i32 s79, 0xfa
	s_movk_i32 s80, 0x3c0
	v_mov_b32_e32 v232, 0xff800000
	s_mov_b32 s81, 0
	s_waitcnt lgkmcnt(0)
	s_barrier
	s_branch .LBB0_1232
